# loop-edge edits in the ATTN k-loop: all-scalar wave-uniform path test (no v_cndmask/readfirstlane ballot), back edge rotated to one taken branch, selection-bit test 3->2 VALU
# speedup vs baseline: 1.0007x; 1.0007x over previous
.LBB0_1455:
	s_and_b32 s36, s2, 1
	s_cmp_gt_i32 s2, s45
	s_cselect_b64 s[0:1], -1, 0
	s_and_b64 s[34:35], s[0:1], exec
	s_cselect_b32 s40, s7, 0
	s_add_i32 s40, s40, s2
	v_readfirstlane_b32 s3, v117
	s_lshl_b32 s50, s40, 6
	s_add_i32 s2, s3, 31
	s_cmp_lt_i32 s2, s50
	s_cbranch_scc1 .LBB0_1470
	s_sub_i32 s3, s3, s50
	s_sub_i32 s3, s3, 63
	s_cmpk_gt_i32 s3, 0x1ff
	s_cselect_b64 s[34:35], -1, 0
	s_and_b64 s[34:35], s[0:1], s[34:35]
	s_and_b64 vcc, exec, s[34:35]
	s_cbranch_vccnz .LBB0_1470
	s_mul_i32 s37, s36, 0x2400
	v_add_u32_e32 v20, s37, v156
	v_add_u32_e32 v21, v20, v157
	v_add_u32_e32 v33, v20, v158
	ds_read_b128 v[134:137], v21
	ds_read_b128 v[138:141], v21 offset:32
	ds_read_b128 v[142:145], v21 offset:64
	ds_read_b128 v[146:149], v21 offset:96
	ds_read_b128 v[236:239], v33
	ds_read_b128 v[240:243], v33 offset:32
	ds_read_b128 v[244:247], v33 offset:64
	ds_read_b128 v[248:251], v33 offset:96
	s_cmpk_gt_i32 s3, 0x70
	s_cselect_b64 s[34:35], -1, 0
	s_and_b64 s[52:53], s[0:1], s[34:35]
	s_sub_i32 s51, s2, s50
	s_cmpk_lt_i32 s51, 0x200
	s_cselect_b64 s[2:3], -1, 0
	s_waitcnt lgkmcnt(7)
	v_mfma_f32_32x32x16_bf16 v[0:15], v[134:137], v[80:83], 0
	s_waitcnt lgkmcnt(6)
	v_mfma_f32_32x32x16_bf16 v[0:15], v[138:141], v[84:87], v[0:15]
	s_waitcnt lgkmcnt(5)
	v_mfma_f32_32x32x16_bf16 v[0:15], v[142:145], v[88:91], v[0:15]
	s_waitcnt lgkmcnt(4)
	v_mfma_f32_32x32x16_bf16 v[0:15], v[146:149], v[92:95], v[0:15]
	s_waitcnt lgkmcnt(3)
	v_mfma_f32_32x32x16_bf16 v[16:31], v[236:239], v[80:83], 0
	s_waitcnt lgkmcnt(2)
	v_mfma_f32_32x32x16_bf16 v[16:31], v[240:243], v[84:87], v[16:31]
	s_waitcnt lgkmcnt(1)
	v_mfma_f32_32x32x16_bf16 v[16:31], v[244:247], v[88:91], v[16:31]
	s_waitcnt lgkmcnt(0)
	v_mfma_f32_32x32x16_bf16 v[16:31], v[248:251], v[92:95], v[16:31]
	s_and_b64 vcc, s[52:53], exec
	s_cselect_b64 s[34:35], s[2:3], s[34:35]
	s_xor_b64 s[34:35], s[34:35], -1
	s_mov_b64 s[2:3], -1
	s_and_b64 vcc, exec, s[34:35]
	s_cbranch_vccz .Lfa_fast
	v_or_b32_e32 v125, s50, v153
	s_cmpk_lt_i32 s51, 0x110
	v_sub_u32_e32 v33, v130, v125
	s_cbranch_scc1 .LBB0_1460
	v_cmp_lt_i32_e32 vcc, s67, v33
	s_and_b64 vcc, s[0:1], vcc
	v_xad_u32 v36, v125, -1, v130
	v_cndmask_b32_e32 v35, 0, v211, vcc
	v_cmp_lt_i32_e32 vcc, s67, v36
	v_or_b32_e32 v38, 2, v125
	s_and_b64 vcc, s[0:1], vcc
	v_sub_u32_e32 v38, v130, v38
	v_med3_i32 v37, v36, -1, v209
	v_cndmask_b32_e32 v36, 0, v211, vcc
	v_med3_i32 v39, v38, -1, v209
	v_cmp_lt_i32_e32 vcc, s67, v38
	v_or_b32_e32 v38, 3, v125
	s_and_b64 vcc, s[0:1], vcc
	v_sub_u32_e32 v38, v130, v38
	v_cndmask_b32_e32 v40, 0, v211, vcc
	v_med3_i32 v41, v38, -1, v209
	v_cmp_lt_i32_e32 vcc, s67, v38
	v_or_b32_e32 v38, 8, v125
	s_and_b64 vcc, s[0:1], vcc
	v_sub_u32_e32 v38, v130, v38
	v_cndmask_b32_e32 v42, 0, v211, vcc
	v_med3_i32 v43, v38, -1, v209
	v_cmp_lt_i32_e32 vcc, s67, v38
	v_or_b32_e32 v38, 9, v125
	s_and_b64 vcc, s[0:1], vcc
	v_sub_u32_e32 v38, v130, v38
	v_cndmask_b32_e32 v44, 0, v211, vcc
	v_med3_i32 v45, v38, -1, v209
	v_cmp_lt_i32_e32 vcc, s67, v38
	v_or_b32_e32 v38, 10, v125
	s_and_b64 vcc, s[0:1], vcc
	v_sub_u32_e32 v38, v130, v38
	v_cndmask_b32_e32 v46, 0, v211, vcc
	v_med3_i32 v47, v38, -1, v209
	v_cmp_lt_i32_e32 vcc, s67, v38
	v_or_b32_e32 v38, 11, v125
	v_sub_u32_e32 v38, v130, v38
	v_med3_i32 v34, v33, -1, v209
	v_med3_i32 v127, v38, -1, v209
	v_lshl_add_u32 v34, v34, 2, s69
	v_lshl_add_u32 v37, v37, 2, s69
	v_lshl_add_u32 v41, v41, 2, s69
	v_lshl_add_u32 v43, v43, 2, s69
	v_lshl_add_u32 v45, v45, 2, s69
	v_lshl_add_u32 v47, v47, 2, s69
	v_lshl_add_u32 v127, v127, 2, s69
	v_lshl_add_u32 v39, v39, 2, s69
	ds_read_b32 v34, v34 offset:256
	ds_read_b32 v37, v37 offset:256
	ds_read_b32 v129, v39 offset:256
	ds_read_b32 v41, v41 offset:256
	ds_read_b32 v43, v43 offset:256
	ds_read_b32 v45, v45 offset:256
	ds_read_b32 v47, v47 offset:256
	ds_read_b32 v127, v127 offset:256
	s_and_b64 vcc, s[0:1], vcc
	v_cndmask_b32_e32 v131, 0, v211, vcc
	v_cmp_lt_i32_e32 vcc, s67, v38
	s_and_b64 vcc, s[0:1], vcc
	s_nop 0
	v_cndmask_b32_e32 v134, 0, v211, vcc
	s_waitcnt lgkmcnt(7)
	v_fmac_f32_e32 v34, 0x3fb8aa3b, v0
	s_waitcnt lgkmcnt(6)
	v_fmac_f32_e32 v37, 0x3fb8aa3b, v1
	v_add_f32_e32 v38, v35, v34
	v_add_f32_e32 v39, v36, v37
	s_waitcnt lgkmcnt(5)
	v_fmac_f32_e32 v129, 0x3fb8aa3b, v2
	s_waitcnt lgkmcnt(4)
	v_fmac_f32_e32 v41, 0x3fb8aa3b, v3
	v_max3_f32 v34, v38, s70, v39
	v_add_f32_e32 v36, v40, v129
	v_add_f32_e32 v37, v42, v41
	s_waitcnt lgkmcnt(3)
	v_fmac_f32_e32 v43, 0x3fb8aa3b, v4
	s_waitcnt lgkmcnt(2)
	v_fmac_f32_e32 v45, 0x3fb8aa3b, v5
	v_max3_f32 v34, v34, v36, v37
	v_add_f32_e32 v40, v44, v43
	v_add_f32_e32 v41, v46, v45
	s_waitcnt lgkmcnt(1)
	v_fmac_f32_e32 v47, 0x3fb8aa3b, v6
	s_waitcnt lgkmcnt(0)
	v_fmac_f32_e32 v127, 0x3fb8aa3b, v7
	v_max3_f32 v42, v34, v40, v41
	v_add_f32_e32 v34, v131, v47
	v_add_f32_e32 v35, v134, v127
	v_max3_f32 v42, v42, v34, v35
	v_or_b32_e32 v43, 16, v125
	v_sub_u32_e32 v43, v130, v43
	v_cmp_lt_i32_e32 vcc, s67, v43
	v_or_b32_e32 v45, 17, v125
	s_and_b64 vcc, s[0:1], vcc
	v_sub_u32_e32 v45, v130, v45
	v_med3_i32 v44, v43, -1, v209
	v_cndmask_b32_e32 v43, 0, v211, vcc
	v_cmp_lt_i32_e32 vcc, s67, v45
	v_or_b32_e32 v47, 18, v125
	s_and_b64 vcc, s[0:1], vcc
	v_sub_u32_e32 v47, v130, v47
	v_med3_i32 v46, v45, -1, v209
	v_cndmask_b32_e32 v45, 0, v211, vcc
	v_cmp_lt_i32_e32 vcc, s67, v47
	v_or_b32_e32 v129, 19, v125
	s_and_b64 vcc, s[0:1], vcc
	v_sub_u32_e32 v129, v130, v129
	v_med3_i32 v127, v47, -1, v209
	v_cndmask_b32_e32 v47, 0, v211, vcc
	v_cmp_lt_i32_e32 vcc, s67, v129
	v_or_b32_e32 v134, 24, v125
	s_and_b64 vcc, s[0:1], vcc
	v_sub_u32_e32 v134, v130, v134
	v_med3_i32 v131, v129, -1, v209
	v_cndmask_b32_e32 v129, 0, v211, vcc
	v_med3_i32 v135, v134, -1, v209
	v_cmp_lt_i32_e32 vcc, s67, v134
	v_or_b32_e32 v134, 25, v125
	s_and_b64 vcc, s[0:1], vcc
	v_sub_u32_e32 v134, v130, v134
	v_cndmask_b32_e32 v136, 0, v211, vcc
	v_med3_i32 v137, v134, -1, v209
	v_cmp_lt_i32_e32 vcc, s67, v134
	v_or_b32_e32 v134, 26, v125
	s_and_b64 vcc, s[0:1], vcc
	v_sub_u32_e32 v134, v130, v134
	v_cndmask_b32_e32 v138, 0, v211, vcc
	v_med3_i32 v139, v134, -1, v209
	v_cmp_lt_i32_e32 vcc, s67, v134
	v_or_b32_e32 v134, 27, v125
	v_sub_u32_e32 v134, v130, v134
	v_med3_i32 v140, v134, -1, v209
	v_lshl_add_u32 v44, v44, 2, s69
	v_lshl_add_u32 v46, v46, 2, s69
	v_lshl_add_u32 v127, v127, 2, s69
	v_lshl_add_u32 v131, v131, 2, s69
	v_lshl_add_u32 v137, v137, 2, s69
	v_lshl_add_u32 v139, v139, 2, s69
	v_lshl_add_u32 v140, v140, 2, s69
	v_lshl_add_u32 v135, v135, 2, s69
	ds_read_b32 v44, v44 offset:256
	ds_read_b32 v46, v46 offset:256
	ds_read_b32 v127, v127 offset:256
	ds_read_b32 v131, v131 offset:256
	ds_read_b32 v141, v135 offset:256
	ds_read_b32 v137, v137 offset:256
	ds_read_b32 v139, v139 offset:256
	ds_read_b32 v140, v140 offset:256
	s_and_b64 vcc, s[0:1], vcc
	v_cndmask_b32_e32 v142, 0, v211, vcc
	v_cmp_lt_i32_e32 vcc, s67, v134
	s_and_b64 vcc, s[0:1], vcc
	s_nop 0
	v_cndmask_b32_e32 v143, 0, v211, vcc
	s_waitcnt lgkmcnt(7)
	v_fmac_f32_e32 v44, 0x3fb8aa3b, v8
	s_waitcnt lgkmcnt(6)
	v_fmac_f32_e32 v46, 0x3fb8aa3b, v9
	v_add_f32_e32 v134, v43, v44
	v_add_f32_e32 v135, v45, v46
	s_waitcnt lgkmcnt(5)
	v_fmac_f32_e32 v127, 0x3fb8aa3b, v10
	s_waitcnt lgkmcnt(4)
	v_fmac_f32_e32 v131, 0x3fb8aa3b, v11
	v_max3_f32 v42, v42, v134, v135
	v_add_f32_e32 v44, v47, v127
	v_add_f32_e32 v45, v129, v131
	s_waitcnt lgkmcnt(3)
	v_fmac_f32_e32 v141, 0x3fb8aa3b, v12
	s_waitcnt lgkmcnt(2)
	v_fmac_f32_e32 v137, 0x3fb8aa3b, v13
	v_max3_f32 v42, v42, v44, v45
	v_add_f32_e32 v46, v136, v141
	v_add_f32_e32 v47, v138, v137
	s_waitcnt lgkmcnt(1)
	v_fmac_f32_e32 v139, 0x3fb8aa3b, v14
	s_waitcnt lgkmcnt(0)
	v_fmac_f32_e32 v140, 0x3fb8aa3b, v15
	v_max3_f32 v127, v42, v46, v47
	v_add_f32_e32 v42, v142, v139
	v_add_f32_e32 v43, v143, v140
	v_max3_f32 v127, v127, v42, v43
	v_or_b32_e32 v129, 32, v125
	v_sub_u32_e32 v129, v130, v129
	v_cmp_lt_i32_e32 vcc, s67, v129
	v_or_b32_e32 v136, 33, v125
	s_and_b64 vcc, s[0:1], vcc
	v_sub_u32_e32 v136, v130, v136
	v_med3_i32 v131, v129, -1, v209
	v_cndmask_b32_e32 v129, 0, v211, vcc
	v_cmp_lt_i32_e32 vcc, s67, v136
	v_or_b32_e32 v138, 34, v125
	s_and_b64 vcc, s[0:1], vcc
	v_sub_u32_e32 v138, v130, v138
	v_med3_i32 v137, v136, -1, v209
	v_cndmask_b32_e32 v136, 0, v211, vcc
	v_cmp_lt_i32_e32 vcc, s67, v138
	v_or_b32_e32 v140, 35, v125
	s_and_b64 vcc, s[0:1], vcc
	v_sub_u32_e32 v140, v130, v140
	v_med3_i32 v139, v138, -1, v209
	v_cndmask_b32_e32 v138, 0, v211, vcc
	v_cmp_lt_i32_e32 vcc, s67, v140
	v_or_b32_e32 v142, 40, v125
	s_and_b64 vcc, s[0:1], vcc
	v_sub_u32_e32 v142, v130, v142
	v_med3_i32 v141, v140, -1, v209
	v_cndmask_b32_e32 v140, 0, v211, vcc
	v_med3_i32 v143, v142, -1, v209
	v_cmp_lt_i32_e32 vcc, s67, v142
	v_or_b32_e32 v142, 41, v125
	s_and_b64 vcc, s[0:1], vcc
	v_sub_u32_e32 v142, v130, v142
	v_cndmask_b32_e32 v144, 0, v211, vcc
	v_med3_i32 v145, v142, -1, v209
	v_cmp_lt_i32_e32 vcc, s67, v142
	v_or_b32_e32 v142, 42, v125
	s_and_b64 vcc, s[0:1], vcc
	v_sub_u32_e32 v142, v130, v142
	v_cndmask_b32_e32 v146, 0, v211, vcc
	v_med3_i32 v147, v142, -1, v209
	v_cmp_lt_i32_e32 vcc, s67, v142
	v_or_b32_e32 v142, 43, v125
	v_sub_u32_e32 v142, v130, v142
	v_med3_i32 v148, v142, -1, v209
	v_lshl_add_u32 v131, v131, 2, s69
	v_lshl_add_u32 v137, v137, 2, s69
	v_lshl_add_u32 v139, v139, 2, s69
	v_lshl_add_u32 v141, v141, 2, s69
	v_lshl_add_u32 v145, v145, 2, s69
	v_lshl_add_u32 v147, v147, 2, s69
	v_lshl_add_u32 v148, v148, 2, s69
	v_lshl_add_u32 v143, v143, 2, s69
	ds_read_b32 v131, v131 offset:256
	ds_read_b32 v137, v137 offset:256
	ds_read_b32 v139, v139 offset:256
	ds_read_b32 v141, v141 offset:256
	ds_read_b32 v149, v143 offset:256
	ds_read_b32 v145, v145 offset:256
	ds_read_b32 v147, v147 offset:256
	ds_read_b32 v148, v148 offset:256
	s_and_b64 vcc, s[0:1], vcc
	v_cndmask_b32_e32 v150, 0, v211, vcc
	v_cmp_lt_i32_e32 vcc, s67, v142
	s_and_b64 vcc, s[0:1], vcc
	s_nop 0
	v_cndmask_b32_e32 v151, 0, v211, vcc
	s_waitcnt lgkmcnt(7)
	v_fmac_f32_e32 v131, 0x3fb8aa3b, v16
	s_waitcnt lgkmcnt(6)
	v_fmac_f32_e32 v137, 0x3fb8aa3b, v17
	v_add_f32_e32 v142, v129, v131
	v_add_f32_e32 v143, v136, v137
	s_waitcnt lgkmcnt(5)
	v_fmac_f32_e32 v139, 0x3fb8aa3b, v18
	s_waitcnt lgkmcnt(4)
	v_fmac_f32_e32 v141, 0x3fb8aa3b, v19
	v_max3_f32 v127, v127, v142, v143
	v_add_f32_e32 v138, v138, v139
	v_add_f32_e32 v139, v140, v141
	s_waitcnt lgkmcnt(3)
	v_fmac_f32_e32 v149, 0x3fb8aa3b, v20
	s_waitcnt lgkmcnt(2)
	v_fmac_f32_e32 v145, 0x3fb8aa3b, v21
	v_max3_f32 v127, v127, v138, v139
	v_add_f32_e32 v140, v144, v149
	v_add_f32_e32 v141, v146, v145
	s_waitcnt lgkmcnt(1)
	v_fmac_f32_e32 v147, 0x3fb8aa3b, v22
	s_waitcnt lgkmcnt(0)
	v_fmac_f32_e32 v148, 0x3fb8aa3b, v23
	v_max3_f32 v127, v127, v140, v141
	v_add_f32_e32 v136, v150, v147
	v_add_f32_e32 v137, v151, v148
	v_max3_f32 v127, v127, v136, v137
	v_or_b32_e32 v129, 48, v125
	v_sub_u32_e32 v129, v130, v129
	v_cmp_lt_i32_e32 vcc, s67, v129
	v_or_b32_e32 v144, 49, v125
	s_and_b64 vcc, s[0:1], vcc
	v_sub_u32_e32 v144, v130, v144
	v_med3_i32 v131, v129, -1, v209
	v_cndmask_b32_e32 v129, 0, v211, vcc
	v_cmp_lt_i32_e32 vcc, s67, v144
	v_or_b32_e32 v146, 50, v125
	s_and_b64 vcc, s[0:1], vcc
	v_sub_u32_e32 v146, v130, v146
	v_med3_i32 v145, v144, -1, v209
	v_cndmask_b32_e32 v144, 0, v211, vcc
	v_cmp_lt_i32_e32 vcc, s67, v146
	v_or_b32_e32 v148, 51, v125
	s_and_b64 vcc, s[0:1], vcc
	v_sub_u32_e32 v148, v130, v148
	v_med3_i32 v147, v146, -1, v209
	v_cndmask_b32_e32 v146, 0, v211, vcc
	v_cmp_lt_i32_e32 vcc, s67, v148
	v_or_b32_e32 v150, 56, v125
	s_and_b64 vcc, s[0:1], vcc
	v_sub_u32_e32 v150, v130, v150
	v_med3_i32 v149, v148, -1, v209
	v_cndmask_b32_e32 v148, 0, v211, vcc
	v_med3_i32 v151, v150, -1, v209
	v_cmp_lt_i32_e32 vcc, s67, v150
	v_or_b32_e32 v150, 57, v125
	s_and_b64 vcc, s[0:1], vcc
	v_sub_u32_e32 v150, v130, v150
	v_cndmask_b32_e32 v213, 0, v211, vcc
	v_med3_i32 v214, v150, -1, v209
	v_cmp_lt_i32_e32 vcc, s67, v150
	v_or_b32_e32 v150, 58, v125
	v_sub_u32_e32 v150, v130, v150
	v_or_b32_e32 v125, 59, v125
	s_and_b64 vcc, s[0:1], vcc
	v_med3_i32 v216, v150, -1, v209
	v_sub_u32_e32 v125, v130, v125
	v_lshl_add_u32 v131, v131, 2, s69
	v_lshl_add_u32 v145, v145, 2, s69
	v_lshl_add_u32 v147, v147, 2, s69
	v_lshl_add_u32 v149, v149, 2, s69
	v_lshl_add_u32 v214, v214, 2, s69
	v_cndmask_b32_e32 v215, 0, v211, vcc
	v_lshl_add_u32 v216, v216, 2, s69
	v_cmp_lt_i32_e32 vcc, s67, v150
	v_med3_i32 v150, v125, -1, v209
	v_lshl_add_u32 v151, v151, 2, s69
	v_lshl_add_u32 v150, v150, 2, s69
	ds_read_b32 v131, v131 offset:256
	ds_read_b32 v145, v145 offset:256
	ds_read_b32 v147, v147 offset:256
	ds_read_b32 v149, v149 offset:256
	ds_read_b32 v217, v151 offset:256
	ds_read_b32 v214, v214 offset:256
	ds_read_b32 v216, v216 offset:256
	ds_read_b32 v218, v150 offset:256
	s_and_b64 vcc, s[0:1], vcc
	v_cndmask_b32_e32 v219, 0, v211, vcc
	v_cmp_lt_i32_e32 vcc, s67, v125
	s_and_b64 vcc, s[0:1], vcc
	s_nop 0
	v_cndmask_b32_e32 v125, 0, v211, vcc
	s_waitcnt lgkmcnt(7)
	v_fmac_f32_e32 v131, 0x3fb8aa3b, v24
	s_waitcnt lgkmcnt(6)
	v_fmac_f32_e32 v145, 0x3fb8aa3b, v25
	v_add_f32_e32 v150, v129, v131
	v_add_f32_e32 v151, v144, v145
	s_waitcnt lgkmcnt(5)
	v_fmac_f32_e32 v147, 0x3fb8aa3b, v26
	s_waitcnt lgkmcnt(4)
	v_fmac_f32_e32 v149, 0x3fb8aa3b, v27
	v_max3_f32 v127, v127, v150, v151
	v_add_f32_e32 v146, v146, v147
	v_add_f32_e32 v147, v148, v149
	s_waitcnt lgkmcnt(3)
	v_fmac_f32_e32 v217, 0x3fb8aa3b, v28
	s_waitcnt lgkmcnt(2)
	v_fmac_f32_e32 v214, 0x3fb8aa3b, v29
	v_max3_f32 v127, v127, v146, v147
	v_add_f32_e32 v148, v213, v217
	v_add_f32_e32 v149, v215, v214
	s_waitcnt lgkmcnt(1)
	v_fmac_f32_e32 v216, 0x3fb8aa3b, v30
	s_waitcnt lgkmcnt(0)
	v_fmac_f32_e32 v218, 0x3fb8aa3b, v31
	v_max3_f32 v127, v127, v148, v149
	v_add_f32_e32 v144, v219, v216
	v_add_f32_e32 v145, v125, v218
	v_max3_f32 v129, v127, v144, v145
	s_mov_b64 s[2:3], 0

.LBB0_1465:
	s_lshl_b32 s100, 1, s40
	v_and_b32_e32 v0, s100, v104
	v_cmp_ne_u32_e32 vcc, 0, v0
	s_or_b64 s[0:1], s[0:1], vcc
	v_cndmask_b32_e64 v0, v211, v129, s[0:1]
	ds_bpermute_b32 v1, v155, v0
	v_add_u32_e32 v252, s37, v204
	ds_read_b64_tr_b16 v[236:237], v252 offset:18432
	ds_read_b64_tr_b16 v[238:239], v252 offset:19584
	ds_read_b64_tr_b16 v[240:241], v252 offset:18496
	ds_read_b64_tr_b16 v[242:243], v252 offset:19648
	ds_read_b64_tr_b16 v[244:245], v252 offset:20736
	ds_read_b64_tr_b16 v[246:247], v252 offset:21888
	ds_read_b64_tr_b16 v[248:249], v252 offset:20800
	ds_read_b64_tr_b16 v[250:251], v252 offset:21952
	s_mov_b64 s[2:3], -1
	s_waitcnt lgkmcnt(8)
	v_max3_f32 v33, v123, v0, v1
	v_sub_f32_e32 v253, v33, v123
	v_cmp_neq_f32_e64 s[98:99], s70, v123
	v_cmp_lt_f32_e32 vcc, 0x41000000, v253
	s_nop 1
	v_cndmask_b32_e32 v33, v123, v33, vcc
	v_cmp_neq_f32_e32 vcc, s70, v33
	s_nop 1
	v_cndmask_b32_e32 v125, 0, v33, vcc
	v_cndmask_b32_e64 v253, v212, v125, s[0:1]
	v_sub_f32_e32 v0, v38, v253
	v_sub_f32_e32 v1, v39, v253
	v_sub_f32_e32 v2, v36, v253
	v_sub_f32_e32 v3, v37, v253
	v_sub_f32_e32 v4, v40, v253
	v_sub_f32_e32 v5, v41, v253
	v_sub_f32_e32 v6, v34, v253
	v_sub_f32_e32 v7, v35, v253
	v_sub_f32_e32 v8, v134, v253
	v_sub_f32_e32 v9, v135, v253
	v_sub_f32_e32 v10, v44, v253
	v_sub_f32_e32 v11, v45, v253
	v_sub_f32_e32 v12, v46, v253
	v_sub_f32_e32 v13, v47, v253
	v_sub_f32_e32 v14, v42, v253
	v_sub_f32_e32 v15, v43, v253
	v_sub_f32_e32 v16, v142, v253
	v_sub_f32_e32 v17, v143, v253
	v_sub_f32_e32 v18, v138, v253
	v_sub_f32_e32 v19, v139, v253
	v_sub_f32_e32 v20, v140, v253
	v_sub_f32_e32 v21, v141, v253
	v_sub_f32_e32 v22, v136, v253
	v_sub_f32_e32 v23, v137, v253
	v_sub_f32_e32 v24, v150, v253
	v_sub_f32_e32 v25, v151, v253
	v_sub_f32_e32 v26, v146, v253
	v_sub_f32_e32 v27, v147, v253
	v_sub_f32_e32 v28, v148, v253
	v_sub_f32_e32 v29, v149, v253
	v_sub_f32_e32 v30, v144, v253
	v_sub_f32_e32 v31, v145, v253
	v_sub_f32_e32 v34, v123, v125
	v_exp_f32_e32 v34, v34
	s_waitcnt lgkmcnt(6)
	ds_read_b64_tr_b16 v[134:135], v252 offset:23040
	ds_read_b64_tr_b16 v[136:137], v252 offset:24192
	ds_read_b64_tr_b16 v[138:139], v252 offset:23104
	ds_read_b64_tr_b16 v[140:141], v252 offset:24256
	ds_read_b64_tr_b16 v[142:143], v252 offset:25344
	ds_read_b64_tr_b16 v[144:145], v252 offset:26496
	ds_read_b64_tr_b16 v[146:147], v252 offset:25408
	ds_read_b64_tr_b16 v[148:149], v252 offset:26560
	v_cmp_neq_f32_e32 vcc, 1.0, v34
	v_mov_b32_e32 v37, 0
	s_and_b64 vcc, vcc, s[98:99]
	s_cbranch_vccz .Lfa_norescale2
	v_mul_f32_e32 v78, v34, v78
	v_mul_f32_e32 v79, v34, v79
	v_mul_f32_e32 v76, v34, v76
	v_mul_f32_e32 v77, v34, v77
	v_mul_f32_e32 v74, v34, v74
	v_mul_f32_e32 v75, v34, v75
	v_mul_f32_e32 v72, v34, v72
	v_mul_f32_e32 v73, v34, v73
	v_mul_f32_e32 v70, v34, v70
	v_mul_f32_e32 v71, v34, v71
	v_mul_f32_e32 v68, v34, v68
	v_mul_f32_e32 v69, v34, v69
	v_mul_f32_e32 v66, v34, v66
	v_mul_f32_e32 v67, v34, v67
	v_mul_f32_e32 v64, v34, v64
	v_mul_f32_e32 v65, v34, v65
	v_mul_f32_e32 v62, v34, v62
	v_mul_f32_e32 v63, v34, v63
	v_mul_f32_e32 v60, v34, v60
	v_mul_f32_e32 v61, v34, v61
	v_mul_f32_e32 v58, v34, v58
	v_mul_f32_e32 v59, v34, v59
	v_mul_f32_e32 v56, v34, v56
	v_mul_f32_e32 v57, v34, v57
	v_mul_f32_e32 v54, v34, v54
	v_mul_f32_e32 v55, v34, v55
	v_mul_f32_e32 v52, v34, v52
	v_mul_f32_e32 v53, v34, v53
	v_mul_f32_e32 v50, v34, v50
	v_mul_f32_e32 v51, v34, v51
	v_mul_f32_e32 v48, v34, v48
	v_mul_f32_e32 v49, v34, v49

.LBB0_1472:
	s_cmp_eq_u32 s9, s29
	s_mov_b32 s2, s29
	s_waitcnt lgkmcnt(0)
	s_barrier
	s_cbranch_scc0 .LBB0_1451
	s_branch .LBB0_1269
.Lfa_fast:
	v_mov_b32_e32 v33, s69
	ds_read_b32 v127, v33 offset:764
	v_max_f32_e32 v252, v0, v1
	v_max3_f32 v252, v252, v2, v3
	v_max3_f32 v252, v252, v4, v5
	v_max3_f32 v252, v252, v6, v7
	v_max3_f32 v252, v252, v8, v9
	v_max3_f32 v252, v252, v10, v11
	v_max3_f32 v252, v252, v12, v13
	v_max3_f32 v252, v252, v14, v15
	v_max3_f32 v252, v252, v16, v17
	v_max3_f32 v252, v252, v18, v19
	v_max3_f32 v252, v252, v20, v21
	v_max3_f32 v252, v252, v22, v23
	v_max3_f32 v252, v252, v24, v25
	v_max3_f32 v252, v252, v26, v27
	v_max3_f32 v252, v252, v28, v29
	v_max3_f32 v252, v252, v30, v31
	s_lshl_b32 s100, 1, s40
	v_and_b32_e32 v253, s100, v104
	v_cmp_ne_u32_e32 vcc, 0, v253
	s_or_b64 s[0:1], s[0:1], vcc
	s_waitcnt lgkmcnt(0)
	v_fmamk_f32 v129, v252, 0x3fb8aa3b, v127
	v_cndmask_b32_e64 v252, v211, v129, s[0:1]
	ds_bpermute_b32 v253, v155, v252
	v_add_u32_e32 v47, s37, v204
	ds_read_b64_tr_b16 v[134:135], v47 offset:18432
	ds_read_b64_tr_b16 v[136:137], v47 offset:19584
	ds_read_b64_tr_b16 v[138:139], v47 offset:18496
	ds_read_b64_tr_b16 v[140:141], v47 offset:19648
	ds_read_b64_tr_b16 v[142:143], v47 offset:20736
	ds_read_b64_tr_b16 v[144:145], v47 offset:21888
	ds_read_b64_tr_b16 v[146:147], v47 offset:20800
	ds_read_b64_tr_b16 v[148:149], v47 offset:21952
	s_waitcnt lgkmcnt(8)
	v_max3_f32 v33, v123, v252, v253
	v_sub_f32_e32 v34, v33, v123
	v_cmp_neq_f32_e64 s[98:99], s70, v123
	v_cmp_lt_f32_e32 vcc, 0x41000000, v34
	v_mov_b32_e32 v37, 0
	s_nop 0
	v_cndmask_b32_e32 v33, v123, v33, vcc
	v_cmp_neq_f32_e32 vcc, s70, v33
	s_nop 1
	v_cndmask_b32_e32 v125, 0, v33, vcc
	v_sub_f32_e32 v252, v127, v125
	v_cndmask_b32_e64 v36, v211, v252, s[0:1]
	v_sub_f32_e32 v34, v123, v125
	v_exp_f32_e32 v34, v34
	s_waitcnt lgkmcnt(6)
	ds_read_b64_tr_b16 v[236:237], v47 offset:23040
	ds_read_b64_tr_b16 v[238:239], v47 offset:24192
	ds_read_b64_tr_b16 v[240:241], v47 offset:23104
	ds_read_b64_tr_b16 v[242:243], v47 offset:24256
	ds_read_b64_tr_b16 v[244:245], v47 offset:25344
	ds_read_b64_tr_b16 v[246:247], v47 offset:26496
	ds_read_b64_tr_b16 v[248:249], v47 offset:25408
	ds_read_b64_tr_b16 v[250:251], v47 offset:26560
	v_cmp_neq_f32_e32 vcc, 1.0, v34
	s_nop 0
	s_and_b64 vcc, vcc, s[98:99]
	s_cbranch_vccz .Lfa_norescale
	v_mul_f32_e32 v78, v34, v78
	v_mul_f32_e32 v79, v34, v79
	v_mul_f32_e32 v76, v34, v76
	v_mul_f32_e32 v77, v34, v77
	v_mul_f32_e32 v74, v34, v74
	v_mul_f32_e32 v75, v34, v75
	v_mul_f32_e32 v72, v34, v72
	v_mul_f32_e32 v73, v34, v73
	v_mul_f32_e32 v70, v34, v70
	v_mul_f32_e32 v71, v34, v71
	v_mul_f32_e32 v68, v34, v68
	v_mul_f32_e32 v69, v34, v69
	v_mul_f32_e32 v66, v34, v66
	v_mul_f32_e32 v67, v34, v67
	v_mul_f32_e32 v64, v34, v64
	v_mul_f32_e32 v65, v34, v65
	v_mul_f32_e32 v62, v34, v62
	v_mul_f32_e32 v63, v34, v63
	v_mul_f32_e32 v60, v34, v60
	v_mul_f32_e32 v61, v34, v61
	v_mul_f32_e32 v58, v34, v58
	v_mul_f32_e32 v59, v34, v59
	v_mul_f32_e32 v56, v34, v56
	v_mul_f32_e32 v57, v34, v57
	v_mul_f32_e32 v54, v34, v54
	v_mul_f32_e32 v55, v34, v55
	v_mul_f32_e32 v52, v34, v52
	v_mul_f32_e32 v53, v34, v53
	v_mul_f32_e32 v50, v34, v50
	v_mul_f32_e32 v51, v34, v51
	v_mul_f32_e32 v48, v34, v48
	v_mul_f32_e32 v49, v34, v49
